# DF loop off-diagonal tiles: exp/row-sum/bf16-pack of first 32 keys issued in the shadow of the second QK^T MFMA chain (bit-identical math)
# speedup vs baseline: 1.0245x; 1.0175x over previous
; __device__ __forceinline__ void finishSM(f32x16& p0, f32x16& p1, float alpha, float& l_reg, bf16x8& pa0, bf16x8& pa1, bf16x8& pa2, bf16x8& pa3) {
;     float ps = 0;
; #pragma unroll
;     for (int r = 0; r < 16; ++r) ps += p0[r];
; #pragma unroll
;     for (int r = 0; r < 16; ++r) ps += p1[r];
;     { auto rr = __builtin_amdgcn_permlane32_swap(__float_as_uint(ps), __float_as_uint(ps), false, false);
;       ps = __uint_as_float(rr[0]) + __uint_as_float(rr[1]); }
;     l_reg = l_reg * alpha + ps;
;     PK4(p0, 0, pa0); PK4(p0, 8, pa1); PK4(p1, 0, pa2); PK4(p1, 8, pa3);
; template <bool FIXED>
; __device__ __forceinline__ void df_unit(LAS char* lds, bf16_t* QKV, const float* gsub, float lam, float post, int b, int h, int qb, int wave0, float mfix2) {
;     ...
;             if constexpr (FIXED) { constexpr float C2f = LOG2E * SCALE; alpha = 1.f;
; #pragma unroll
;                 for (int r = 0; r < 16; ++r) { p0[r] = __builtin_amdgcn_exp2f(fmaf(p0[r], C2f, mfix2)); p1[r] = __builtin_amdgcn_exp2f(fmaf(p1[r], C2f, mfix2)); } }
.LBB0_143:
	s_nop 1
	v_fmamk_f32 v0, v130, 0x3e0293ee, v231
	s_nop 7
	v_fmamk_f32 v130, v146, 0x3e0293ee, v231
	v_exp_f32_e32 v146, v130
	v_fmamk_f32 v130, v131, 0x3e0293ee, v231
	v_fmamk_f32 v131, v147, 0x3e0293ee, v231
	v_exp_f32_e32 v147, v131
	v_fmamk_f32 v131, v132, 0x3e0293ee, v231
	v_fmamk_f32 v132, v148, 0x3e0293ee, v231
	v_exp_f32_e32 v148, v132
	v_fmamk_f32 v132, v133, 0x3e0293ee, v231
	v_fmamk_f32 v133, v149, 0x3e0293ee, v231
	v_exp_f32_e32 v149, v133
	v_fmamk_f32 v133, v134, 0x3e0293ee, v231
	v_fmamk_f32 v134, v150, 0x3e0293ee, v231
	v_exp_f32_e32 v150, v134
	v_fmamk_f32 v134, v135, 0x3e0293ee, v231
	v_fmamk_f32 v135, v151, 0x3e0293ee, v231
	v_exp_f32_e32 v151, v135
	v_fmamk_f32 v135, v136, 0x3e0293ee, v231
	v_fmamk_f32 v136, v152, 0x3e0293ee, v231
	v_exp_f32_e32 v152, v136
	v_fmamk_f32 v136, v137, 0x3e0293ee, v231
	v_fmamk_f32 v137, v153, 0x3e0293ee, v231
	v_exp_f32_e32 v153, v137
	v_fmamk_f32 v137, v138, 0x3e0293ee, v231
	v_fmamk_f32 v138, v154, 0x3e0293ee, v231
	v_exp_f32_e32 v154, v138
	v_fmamk_f32 v138, v139, 0x3e0293ee, v231
	v_fmamk_f32 v139, v155, 0x3e0293ee, v231
	v_exp_f32_e32 v155, v139
	v_fmamk_f32 v139, v140, 0x3e0293ee, v231
	v_fmamk_f32 v140, v156, 0x3e0293ee, v231
	v_exp_f32_e32 v0, v0
	v_exp_f32_e32 v156, v140
	v_fmamk_f32 v140, v141, 0x3e0293ee, v231
	v_fmamk_f32 v141, v157, 0x3e0293ee, v231
	v_exp_f32_e32 v130, v130
	v_exp_f32_e32 v157, v141
	v_fmamk_f32 v141, v142, 0x3e0293ee, v231
	v_fmamk_f32 v142, v158, 0x3e0293ee, v231
	v_exp_f32_e32 v131, v131
	v_exp_f32_e32 v158, v142
	v_fmamk_f32 v142, v143, 0x3e0293ee, v231
	v_fmamk_f32 v143, v159, 0x3e0293ee, v231
	v_exp_f32_e32 v132, v132
	v_exp_f32_e32 v159, v143
	v_fmamk_f32 v143, v144, 0x3e0293ee, v231
	v_fmamk_f32 v144, v160, 0x3e0293ee, v231
	v_exp_f32_e32 v133, v133
	v_exp_f32_e32 v160, v144
	v_fmamk_f32 v144, v145, 0x3e0293ee, v231
	v_fmamk_f32 v145, v161, 0x3e0293ee, v231
	v_add_f32_e32 v161, 0, v0
	v_exp_f32_e32 v134, v134
	v_add_f32_e32 v161, v130, v161
	v_exp_f32_e32 v135, v135
	v_add_f32_e32 v161, v131, v161
	v_exp_f32_e32 v136, v136
	v_add_f32_e32 v161, v132, v161
	v_exp_f32_e32 v137, v137
	v_add_f32_e32 v161, v133, v161
	v_exp_f32_e32 v138, v138
	v_add_f32_e32 v161, v134, v161
	v_exp_f32_e32 v139, v139
	v_add_f32_e32 v161, v135, v161
	v_exp_f32_e32 v140, v140
	v_add_f32_e32 v161, v136, v161
	v_exp_f32_e32 v141, v141
	v_add_f32_e32 v161, v137, v161
	v_exp_f32_e32 v142, v142
	v_add_f32_e32 v161, v138, v161
	v_exp_f32_e32 v143, v143
	v_add_f32_e32 v161, v139, v161
	v_exp_f32_e32 v144, v144
	v_add_f32_e32 v161, v140, v161
	v_add_f32_e32 v161, v141, v161
	v_add_f32_e32 v161, v142, v161
	v_add_f32_e32 v161, v143, v161
	v_add_f32_e32 v161, v144, v161
	v_add_f32_e32 v161, v146, v161
	v_add_f32_e32 v161, v147, v161
	v_add_f32_e32 v161, v148, v161
	v_add_f32_e32 v161, v149, v161
	v_add_f32_e32 v161, v150, v161
	v_add_f32_e32 v161, v151, v161
	v_add_f32_e32 v161, v152, v161
	v_add_f32_e32 v161, v153, v161
	v_add_f32_e32 v161, v154, v161
	v_add_f32_e32 v161, v155, v161
	v_add_f32_e32 v161, v156, v161
	v_exp_f32_e32 v145, v145
	v_add_f32_e32 v161, v157, v161
	v_add_f32_e32 v161, v158, v161
	v_add_f32_e32 v161, v159, v161
	v_add_f32_e32 v161, v160, v161
	v_add_f32_e32 v161, v145, v161
	v_cvt_pk_bf16_f32 v130, v0, v130
	v_cvt_pk_bf16_f32 v131, v131, v132
	v_cvt_pk_bf16_f32 v132, v133, v134
	v_cvt_pk_bf16_f32 v133, v135, v136
	v_cvt_pk_bf16_f32 v134, v137, v138
	v_cvt_pk_bf16_f32 v135, v139, v140
	v_cvt_pk_bf16_f32 v136, v141, v142
	v_cvt_pk_bf16_f32 v137, v143, v144
	v_cvt_pk_bf16_f32 v138, v146, v147
	v_cvt_pk_bf16_f32 v139, v148, v149
	v_cvt_pk_bf16_f32 v140, v150, v151
	v_cvt_pk_bf16_f32 v141, v152, v153
	v_cvt_pk_bf16_f32 v142, v154, v155
	v_cvt_pk_bf16_f32 v143, v156, v157
	v_cvt_pk_bf16_f32 v144, v158, v159
	v_cvt_pk_bf16_f32 v145, v160, v145
	v_mov_b32_e32 v217, v161
	v_permlane32_swap_b32_e32 v130, v132
	v_permlane32_swap_b32_e32 v131, v133
	v_permlane32_swap_b32_e32 v134, v136
	v_permlane32_swap_b32_e32 v135, v137
	v_permlane32_swap_b32_e32 v138, v140
	v_permlane32_swap_b32_e32 v139, v141
	v_permlane32_swap_b32_e32 v142, v144
	v_permlane32_swap_b32_e32 v143, v145
; #define SBAR() __builtin_amdgcn_sched_barrier(0)
; #define PV_RD(S, d0) do { constexpr int b_ = PV_OFF(d0); TRRD(S##l0, b_); TRRD(S##h0, b_ + 2048); TRRD(S##l1, b_ + 4096); TRRD(S##h1, b_ + 6144); TRRD(S##l2, b_ + 8192); TRRD(S##h2, b_ + 10240); TRRD(S##l3, b_ + 12288); TRRD(S##h3, b_ + 14336); } while (0)
; #define PV_W8() do { asm volatile("s_waitcnt lgkmcnt(8)" ::: "memory"); SBAR(); } while (0)
; #define PV_W0() do { asm volatile("s_waitcnt lgkmcnt(0)" ::: "memory"); SBAR(); } while (0)
; template <int ND0>
; __device__ __forceinline__ void pv_tile2(f32x16* o, unsigned vb, bf16x8 pa0, bf16x8 pa1, bf16x8 pa2, bf16x8 pa3) {
;     ...
;     s16x4 Al0, Al1, Al2, Al3, Ah0, Ah1, Ah2, Ah3, Bl0, Bl1, Bl2, Bl3, Bh0, Bh1, Bh2, Bh3;
;     PV_RD(A, 0);
;     PV_RD(B, 1); PV_W8(); PV_MM(A, 0); SBAR();
;     PV_RD(A, 2); PV_W8(); PV_MM(B, 1); SBAR();
;     if constexpr (ND0 > 4) {
;         PV_RD(B, 3); PV_W8(); PV_MM(A, 2); SBAR();
;         PV_RD(A, 4); PV_W8(); PV_MM(B, 3); SBAR();
;         PV_RD(B, 5); PV_W8(); PV_MM(A, 4); SBAR();
;         PV_RD(A, 6); PV_W8(); PV_MM(B, 5); SBAR();
;         PV_RD(B, 7); PV_W8(); PV_MM(A, 6); SBAR();
;         PV_W0(); PV_MM(B, 7);
; __device__ __forceinline__ void finishSM(f32x16& p0, f32x16& p1, float alpha, float& l_reg, bf16x8& pa0, bf16x8& pa1, bf16x8& pa2, bf16x8& pa3) {
;     ...
;     { auto rr = __builtin_amdgcn_permlane32_swap(__float_as_uint(ps), __float_as_uint(ps), false, false);
;       ps = __uint_as_float(rr[0]) + __uint_as_float(rr[1]); }
;     l_reg = l_reg * alpha + ps;
.Ldf_pv:
	v_add_u32_e32 v0, s4, v214
	ds_read_b64_tr_b16 v[146:147], v0 offset:0
	ds_read_b64_tr_b16 v[148:149], v0 offset:0x800
	ds_read_b64_tr_b16 v[150:151], v0 offset:0x1000
	ds_read_b64_tr_b16 v[152:153], v0 offset:0x1800
	v_mov_b32_e32 v210, v217
	ds_read_b64_tr_b16 v[154:155], v0 offset:0x2000
	s_nop 1
	v_permlane32_swap_b32_e32 v217, v210
	ds_read_b64_tr_b16 v[156:157], v0 offset:0x2800
	v_add_f32_e32 v217, v217, v210
	ds_read_b64_tr_b16 v[158:159], v0 offset:0x3000
	v_add_f32_e32 v216, v216, v217
	ds_read_b64_tr_b16 v[160:161], v0 offset:0x3800
	ds_read_b64_tr_b16 v[210:211], v0 offset:0x200
	ds_read_b64_tr_b16 v[212:213], v0 offset:0xa00
	ds_read_b64_tr_b16 v[218:219], v0 offset:0x1200
	ds_read_b64_tr_b16 v[220:221], v0 offset:0x1a00
	ds_read_b64_tr_b16 v[226:227], v0 offset:0x2200
	ds_read_b64_tr_b16 v[228:229], v0 offset:0x2a00
	ds_read_b64_tr_b16 v[234:235], v0 offset:0x3200
	ds_read_b64_tr_b16 v[236:237], v0 offset:0x3a00
	s_waitcnt lgkmcnt(8)
	s_nop 0
	s_nop 0
	s_nop 0
	s_nop 0
	s_nop 0
	s_nop 0
	s_nop 0
	s_nop 0
	v_mfma_f32_32x32x16_bf16 v[114:129], v[130:133], v[146:149], v[114:129]
	v_mfma_f32_32x32x16_bf16 v[114:129], v[134:137], v[150:153], v[114:129]
	v_mfma_f32_32x32x16_bf16 v[114:129], v[138:141], v[154:157], v[114:129]
	v_mfma_f32_32x32x16_bf16 v[114:129], v[142:145], v[158:161], v[114:129]
	ds_read_b64_tr_b16 v[146:147], v0 offset:0x400
	ds_read_b64_tr_b16 v[148:149], v0 offset:0xc00
	ds_read_b64_tr_b16 v[150:151], v0 offset:0x1400
	ds_read_b64_tr_b16 v[152:153], v0 offset:0x1c00
	ds_read_b64_tr_b16 v[154:155], v0 offset:0x2400
	ds_read_b64_tr_b16 v[156:157], v0 offset:0x2c00
	ds_read_b64_tr_b16 v[158:159], v0 offset:0x3400
	ds_read_b64_tr_b16 v[160:161], v0 offset:0x3c00
	s_waitcnt lgkmcnt(8)
	v_mfma_f32_32x32x16_bf16 v[98:113], v[130:133], v[210:213], v[98:113]
	v_mfma_f32_32x32x16_bf16 v[98:113], v[134:137], v[218:221], v[98:113]
	v_mfma_f32_32x32x16_bf16 v[98:113], v[138:141], v[226:229], v[98:113]
	v_mfma_f32_32x32x16_bf16 v[98:113], v[142:145], v[234:237], v[98:113]
	ds_read_b64_tr_b16 v[210:211], v0 offset:0x600
	ds_read_b64_tr_b16 v[212:213], v0 offset:0xe00
	ds_read_b64_tr_b16 v[218:219], v0 offset:0x1600
	ds_read_b64_tr_b16 v[220:221], v0 offset:0x1e00
	ds_read_b64_tr_b16 v[226:227], v0 offset:0x2600
	ds_read_b64_tr_b16 v[228:229], v0 offset:0x2e00
	ds_read_b64_tr_b16 v[234:235], v0 offset:0x3600
	ds_read_b64_tr_b16 v[236:237], v0 offset:0x3e00
	s_waitcnt lgkmcnt(8)
	v_mfma_f32_32x32x16_bf16 v[82:97], v[130:133], v[146:149], v[82:97]
	v_mfma_f32_32x32x16_bf16 v[82:97], v[134:137], v[150:153], v[82:97]
	v_mfma_f32_32x32x16_bf16 v[82:97], v[138:141], v[154:157], v[82:97]
	v_mfma_f32_32x32x16_bf16 v[82:97], v[142:145], v[158:161], v[82:97]
	ds_read_b64_tr_b16 v[146:147], v0 offset:0x4000
	ds_read_b64_tr_b16 v[148:149], v0 offset:0x4800
	ds_read_b64_tr_b16 v[150:151], v0 offset:0x5000
	ds_read_b64_tr_b16 v[152:153], v0 offset:0x5800
	ds_read_b64_tr_b16 v[154:155], v0 offset:0x6000
	ds_read_b64_tr_b16 v[156:157], v0 offset:0x6800
	ds_read_b64_tr_b16 v[158:159], v0 offset:0x7000
	ds_read_b64_tr_b16 v[160:161], v0 offset:0x7800
	s_waitcnt lgkmcnt(8)
	v_mfma_f32_32x32x16_bf16 v[66:81], v[130:133], v[210:213], v[66:81]
	v_mfma_f32_32x32x16_bf16 v[66:81], v[134:137], v[218:221], v[66:81]
	v_mfma_f32_32x32x16_bf16 v[66:81], v[138:141], v[226:229], v[66:81]
	v_mfma_f32_32x32x16_bf16 v[66:81], v[142:145], v[234:237], v[66:81]
	ds_read_b64_tr_b16 v[210:211], v0 offset:0x4200
	ds_read_b64_tr_b16 v[212:213], v0 offset:0x4a00
	ds_read_b64_tr_b16 v[218:219], v0 offset:0x5200
	ds_read_b64_tr_b16 v[220:221], v0 offset:0x5a00
	ds_read_b64_tr_b16 v[226:227], v0 offset:0x6200
	ds_read_b64_tr_b16 v[228:229], v0 offset:0x6a00
	ds_read_b64_tr_b16 v[234:235], v0 offset:0x7200
	ds_read_b64_tr_b16 v[236:237], v0 offset:0x7a00
	s_waitcnt lgkmcnt(8)
	v_mfma_f32_32x32x16_bf16 v[50:65], v[130:133], v[146:149], v[50:65]
	v_mfma_f32_32x32x16_bf16 v[50:65], v[134:137], v[150:153], v[50:65]
	v_mfma_f32_32x32x16_bf16 v[50:65], v[138:141], v[154:157], v[50:65]
	v_mfma_f32_32x32x16_bf16 v[50:65], v[142:145], v[158:161], v[50:65]
	ds_read_b64_tr_b16 v[146:147], v0 offset:0x4400
	ds_read_b64_tr_b16 v[148:149], v0 offset:0x4c00
	ds_read_b64_tr_b16 v[150:151], v0 offset:0x5400
	ds_read_b64_tr_b16 v[152:153], v0 offset:0x5c00
	ds_read_b64_tr_b16 v[154:155], v0 offset:0x6400
	ds_read_b64_tr_b16 v[156:157], v0 offset:0x6c00
	ds_read_b64_tr_b16 v[158:159], v0 offset:0x7400
	ds_read_b64_tr_b16 v[160:161], v0 offset:0x7c00
	s_waitcnt lgkmcnt(8)
	v_mfma_f32_32x32x16_bf16 v[34:49], v[130:133], v[210:213], v[34:49]
	v_mfma_f32_32x32x16_bf16 v[34:49], v[134:137], v[218:221], v[34:49]
	v_mfma_f32_32x32x16_bf16 v[34:49], v[138:141], v[226:229], v[34:49]
	v_mfma_f32_32x32x16_bf16 v[34:49], v[142:145], v[234:237], v[34:49]
	ds_read_b64_tr_b16 v[210:211], v0 offset:0x4600
	ds_read_b64_tr_b16 v[212:213], v0 offset:0x4e00
	ds_read_b64_tr_b16 v[218:219], v0 offset:0x5600
	ds_read_b64_tr_b16 v[220:221], v0 offset:0x5e00
	ds_read_b64_tr_b16 v[226:227], v0 offset:0x6600
	ds_read_b64_tr_b16 v[228:229], v0 offset:0x6e00
	ds_read_b64_tr_b16 v[234:235], v0 offset:0x7600
	ds_read_b64_tr_b16 v[236:237], v0 offset:0x7e00
	s_waitcnt lgkmcnt(8)
	v_mfma_f32_32x32x16_bf16 v[18:33], v[130:133], v[146:149], v[18:33]
	v_mfma_f32_32x32x16_bf16 v[18:33], v[134:137], v[150:153], v[18:33]
	v_mfma_f32_32x32x16_bf16 v[18:33], v[138:141], v[154:157], v[18:33]
	v_mfma_f32_32x32x16_bf16 v[18:33], v[142:145], v[158:161], v[18:33]
	s_waitcnt lgkmcnt(0)
	v_mfma_f32_32x32x16_bf16 v[2:17], v[130:133], v[210:213], v[2:17]
	v_mfma_f32_32x32x16_bf16 v[2:17], v[134:137], v[218:221], v[2:17]
	v_mfma_f32_32x32x16_bf16 v[2:17], v[138:141], v[226:229], v[2:17]
	v_mfma_f32_32x32x16_bf16 v[2:17], v[142:145], v[234:237], v[2:17]

; __device__ __forceinline__ int crow(int r, int hi) { return (r & 3) + 8 * (r >> 2) + 4 * hi; }
; __device__ __forceinline__ void finishSM(f32x16& p0, f32x16& p1, float alpha, float& l_reg, bf16x8& pa0, bf16x8& pa1, bf16x8& pa2, bf16x8& pa3) {
;     float ps = 0;
; #pragma unroll
;     for (int r = 0; r < 16; ++r) ps += p0[r];
; #pragma unroll
;     for (int r = 0; r < 16; ++r) ps += p1[r];
;     { auto rr = __builtin_amdgcn_permlane32_swap(__float_as_uint(ps), __float_as_uint(ps), false, false);
;       ps = __uint_as_float(rr[0]) + __uint_as_float(rr[1]); }
;     l_reg = l_reg * alpha + ps;
;     PK4(p0, 0, pa0); PK4(p0, 8, pa1); PK4(p1, 0, pa2); PK4(p1, 8, pa3);
; template <bool FIXED>
; __device__ __forceinline__ void df_unit(LAS char* lds, bf16_t* QKV, const float* gsub, float lam, float post, int b, int h, int qb, int wave0, float mfix2) {
;     ...
;         if (kb <= qlo + 31) {
;             f32x16 p0, p1; bf16x8 pa0, pa1, pa2, pa3; float alpha;
;             qkt_b<false>(p0, p1, (unsigned)(size_t)(lds + bf * 4 * TILE + mp * TILE), r32, hi, qr);
;             if (kb + 63 > qlo) mask_incl(p0, p1, qm - kb);
;             if constexpr (FIXED) { constexpr float C2f = LOG2E * SCALE; alpha = 1.f;
; #pragma unroll
;                 for (int r = 0; r < 16; ++r) { p0[r] = __builtin_amdgcn_exp2f(fmaf(p0[r], C2f, mfix2)); p1[r] = __builtin_amdgcn_exp2f(fmaf(p1[r], C2f, mfix2)); } }
;             else {
;             partialSM(p0, p1, m_reg, alpha);
;             if (__any(alpha < 1.f)) { if (hi == 0) al_l[r32] = alpha; asm volatile("s_waitcnt lgkmcnt(0)" ::: "memory");
; #pragma unroll
;                 for (int r = 0; r < 16; ++r) { const float a = al_l[crow(r, hi)];
; #pragma unroll
;                     for (int d = 0; d < 8; ++d) o[d][r] *= a; } }
;             }
;             finishSM(p0, p1, alpha, l_reg, pa0, pa1, pa2, pa3);
;             pv_tile2<8>(o, vbase + bf * 4 * TILE + 2 * TILE, pa0, pa1, pa2, pa3);
.LBB0_147:
	s_sub_i32 s1, s19, 63
	s_cmp_gt_u32 s1, s33
	s_cbranch_scc1 .LBB0_144
	s_lshl_b32 s4, s0, 16
	s_add_i32 s0, s34, s4
	v_add_u32_e32 v0, s0, v206
	ds_read_b128 v[130:133], v0 offset:0
	v_add_u32_e32 v210, s0, v207
	ds_read_b128 v[146:149], v210 offset:0
	v_add_u32_e32 v217, s0, v208
	ds_read_b128 v[150:153], v217 offset:0
	v_add_u32_e32 v233, s0, v209
	ds_read_b128 v[154:157], v233 offset:0
	ds_read_b128 v[158:161], v0 offset:0x80
	ds_read_b128 v[218:221], v210 offset:0x80
	ds_read_b128 v[234:237], v217 offset:0x80
	ds_read_b128 v[238:241], v233 offset:0x80
	s_waitcnt lgkmcnt(0)
	v_mfma_f32_32x32x16_bf16 v[130:145], v[130:133], v[162:165], 0
	v_mfma_f32_32x32x16_bf16 v[130:145], v[146:149], v[166:169], v[130:145]
	v_mfma_f32_32x32x16_bf16 v[130:145], v[150:153], v[170:173], v[130:145]
	v_mfma_f32_32x32x16_bf16 v[130:145], v[154:157], v[174:177], v[130:145]
	v_mfma_f32_32x32x16_bf16 v[130:145], v[158:161], v[178:181], v[130:145]
	v_mfma_f32_32x32x16_bf16 v[130:145], v[218:221], v[182:185], v[130:145]
	v_mfma_f32_32x32x16_bf16 v[130:145], v[234:237], v[186:189], v[130:145]
	v_mfma_f32_32x32x16_bf16 v[130:145], v[238:241], v[190:193], v[130:145]
	ds_read_b128 v[146:149], v0 offset:0x2000
	ds_read_b128 v[218:221], v210 offset:0x2000
	ds_read_b128 v[234:237], v217 offset:0x2000
	ds_read_b128 v[238:241], v233 offset:0x2000
	ds_read_b128 v[242:245], v0 offset:0x2080
	ds_read_b128 v[246:249], v210 offset:0x2080
	ds_read_b128 v[210:213], v217 offset:0x2080
	ds_read_b128 v[226:229], v233 offset:0x2080
	s_cmp_le_u32 s19, s15
	s_waitcnt lgkmcnt(0)
	s_cbranch_scc0 .Ldf_diag
	s_nop 0
	v_mfma_f32_32x32x16_bf16 v[146:161], v[146:149], v[162:165], 0
	v_mfma_f32_32x32x16_bf16 v[146:161], v[218:221], v[166:169], v[146:161]
	v_fmamk_f32 v130, v130, 0x3e0293ee, v231
	v_fmamk_f32 v131, v131, 0x3e0293ee, v231
	v_exp_f32_e32 v130, v130
	v_exp_f32_e32 v131, v131
	v_mfma_f32_32x32x16_bf16 v[146:161], v[234:237], v[170:173], v[146:161]
	v_fmamk_f32 v132, v132, 0x3e0293ee, v231
	v_fmamk_f32 v133, v133, 0x3e0293ee, v231
	v_exp_f32_e32 v132, v132
	v_exp_f32_e32 v133, v133
	v_add_f32_e32 v217, 0, v130
	v_add_f32_e32 v217, v131, v217
	v_mfma_f32_32x32x16_bf16 v[146:161], v[238:241], v[174:177], v[146:161]
	v_fmamk_f32 v134, v134, 0x3e0293ee, v231
	v_fmamk_f32 v135, v135, 0x3e0293ee, v231
	v_exp_f32_e32 v134, v134
	v_exp_f32_e32 v135, v135
	v_add_f32_e32 v217, v132, v217
	v_add_f32_e32 v217, v133, v217
	v_mfma_f32_32x32x16_bf16 v[146:161], v[242:245], v[178:181], v[146:161]
	v_fmamk_f32 v136, v136, 0x3e0293ee, v231
	v_fmamk_f32 v137, v137, 0x3e0293ee, v231
	v_exp_f32_e32 v136, v136
	v_exp_f32_e32 v137, v137
	v_add_f32_e32 v217, v134, v217
	v_add_f32_e32 v217, v135, v217
	v_mfma_f32_32x32x16_bf16 v[146:161], v[246:249], v[182:185], v[146:161]
	v_fmamk_f32 v138, v138, 0x3e0293ee, v231
	v_fmamk_f32 v139, v139, 0x3e0293ee, v231
	v_exp_f32_e32 v138, v138
	v_exp_f32_e32 v139, v139
	v_add_f32_e32 v217, v136, v217
	v_add_f32_e32 v217, v137, v217
	v_mfma_f32_32x32x16_bf16 v[146:161], v[210:213], v[186:189], v[146:161]
	v_fmamk_f32 v140, v140, 0x3e0293ee, v231
	v_fmamk_f32 v141, v141, 0x3e0293ee, v231
	v_exp_f32_e32 v140, v140
	v_exp_f32_e32 v141, v141
	v_add_f32_e32 v217, v138, v217
	v_add_f32_e32 v217, v139, v217
	v_mfma_f32_32x32x16_bf16 v[146:161], v[226:229], v[190:193], v[146:161]
	v_fmamk_f32 v142, v142, 0x3e0293ee, v231
	v_fmamk_f32 v143, v143, 0x3e0293ee, v231
	v_exp_f32_e32 v142, v142
	v_exp_f32_e32 v143, v143
	v_add_f32_e32 v217, v140, v217
	v_add_f32_e32 v217, v141, v217
	v_fmamk_f32 v144, v144, 0x3e0293ee, v231
	v_fmamk_f32 v145, v145, 0x3e0293ee, v231
	v_exp_f32_e32 v144, v144
	v_exp_f32_e32 v145, v145
	v_add_f32_e32 v217, v142, v217
	v_add_f32_e32 v217, v143, v217
	v_add_f32_e32 v217, v144, v217
	v_add_f32_e32 v217, v145, v217
	v_cvt_pk_bf16_f32 v130, v130, v131
	v_cvt_pk_bf16_f32 v131, v132, v133
	v_cvt_pk_bf16_f32 v132, v134, v135
	v_cvt_pk_bf16_f32 v133, v136, v137
	v_cvt_pk_bf16_f32 v134, v138, v139
	v_cvt_pk_bf16_f32 v135, v140, v141
	v_cvt_pk_bf16_f32 v136, v142, v143
	v_cvt_pk_bf16_f32 v137, v144, v145
	v_permlane32_swap_b32_e32 v130, v132
	v_permlane32_swap_b32_e32 v131, v133
	v_permlane32_swap_b32_e32 v134, v136
	v_permlane32_swap_b32_e32 v135, v137
	v_fmamk_f32 v146, v146, 0x3e0293ee, v231
	v_fmamk_f32 v147, v147, 0x3e0293ee, v231
	v_exp_f32_e32 v146, v146
	v_exp_f32_e32 v147, v147
	v_fmamk_f32 v148, v148, 0x3e0293ee, v231
	v_fmamk_f32 v149, v149, 0x3e0293ee, v231
	v_exp_f32_e32 v148, v148
	v_exp_f32_e32 v149, v149
	v_add_f32_e32 v217, v146, v217
	v_add_f32_e32 v217, v147, v217
	v_fmamk_f32 v150, v150, 0x3e0293ee, v231
	v_fmamk_f32 v151, v151, 0x3e0293ee, v231
	v_exp_f32_e32 v150, v150
	v_exp_f32_e32 v151, v151
	v_add_f32_e32 v217, v148, v217
	v_add_f32_e32 v217, v149, v217
	v_fmamk_f32 v152, v152, 0x3e0293ee, v231
	v_fmamk_f32 v153, v153, 0x3e0293ee, v231
	v_exp_f32_e32 v152, v152
	v_exp_f32_e32 v153, v153
	v_add_f32_e32 v217, v150, v217
	v_add_f32_e32 v217, v151, v217
	v_fmamk_f32 v154, v154, 0x3e0293ee, v231
	v_fmamk_f32 v155, v155, 0x3e0293ee, v231
	v_exp_f32_e32 v154, v154
	v_exp_f32_e32 v155, v155
	v_add_f32_e32 v217, v152, v217
	v_add_f32_e32 v217, v153, v217
	v_fmamk_f32 v156, v156, 0x3e0293ee, v231
	v_fmamk_f32 v157, v157, 0x3e0293ee, v231
	v_exp_f32_e32 v156, v156
	v_exp_f32_e32 v157, v157
	v_add_f32_e32 v217, v154, v217
	v_add_f32_e32 v217, v155, v217
	v_fmamk_f32 v158, v158, 0x3e0293ee, v231
	v_fmamk_f32 v159, v159, 0x3e0293ee, v231
	v_exp_f32_e32 v158, v158
	v_exp_f32_e32 v159, v159
	v_add_f32_e32 v217, v156, v217
	v_add_f32_e32 v217, v157, v217
	v_fmamk_f32 v160, v160, 0x3e0293ee, v231
	v_fmamk_f32 v161, v161, 0x3e0293ee, v231
	v_exp_f32_e32 v160, v160
	v_exp_f32_e32 v161, v161
	v_add_f32_e32 v217, v158, v217
	v_add_f32_e32 v217, v159, v217
	s_nop 0
	v_add_f32_e32 v217, v160, v217
	v_add_f32_e32 v217, v161, v217
	v_cvt_pk_bf16_f32 v138, v146, v147
	v_cvt_pk_bf16_f32 v139, v148, v149
	v_cvt_pk_bf16_f32 v140, v150, v151
	v_cvt_pk_bf16_f32 v141, v152, v153
	v_cvt_pk_bf16_f32 v142, v154, v155
	v_cvt_pk_bf16_f32 v143, v156, v157
	v_cvt_pk_bf16_f32 v144, v158, v159
	v_cvt_pk_bf16_f32 v145, v160, v161
	s_nop 0
	v_permlane32_swap_b32_e32 v138, v140
	v_permlane32_swap_b32_e32 v139, v141
	v_permlane32_swap_b32_e32 v142, v144
	v_permlane32_swap_b32_e32 v143, v145
	s_branch .Ldf_pv
; #define SBAR() __builtin_amdgcn_sched_barrier(0)
; template <bool ALL16>
; __device__ __forceinline__ void qkt_b(f32x16& p0, f32x16& p1, unsigned kt, int r32, int hi, const bf16x8* qr) {
;     ...
;         asm volatile("s_waitcnt lgkmcnt(0)" ::: "memory"); SBAR();
;         KMMA8(p1, a);
; __device__ __forceinline__ void mask_incl(f32x16& p0, f32x16& p1, int dq) {
;     const float NEG = -__builtin_inff();
; #pragma unroll
;     for (int r = 0; r < 16; ++r) { const int c = (r & 3) + 8 * (r >> 2);
;         if (dq - c < 0) p0[r] = NEG;
;         if (dq - c - 32 < 0) p1[r] = NEG; }
; }
.Ldf_diag:
	s_nop 0
	v_mfma_f32_32x32x16_bf16 v[146:161], v[146:149], v[162:165], 0
	v_mfma_f32_32x32x16_bf16 v[146:161], v[218:221], v[166:169], v[146:161]
	v_mfma_f32_32x32x16_bf16 v[146:161], v[234:237], v[170:173], v[146:161]
	v_mfma_f32_32x32x16_bf16 v[146:161], v[238:241], v[174:177], v[146:161]
	v_mfma_f32_32x32x16_bf16 v[146:161], v[242:245], v[178:181], v[146:161]
	v_mfma_f32_32x32x16_bf16 v[146:161], v[246:249], v[182:185], v[146:161]
	v_mfma_f32_32x32x16_bf16 v[146:161], v[210:213], v[186:189], v[146:161]
	v_mfma_f32_32x32x16_bf16 v[146:161], v[226:229], v[190:193], v[146:161]
	v_cmp_gt_i32_e64 s[94:95], 26, v215
	v_cmp_gt_i32_e64 s[96:97], 27, v215
	v_cmp_gt_i32_e64 s[92:93], 25, v215
	s_and_b64 s[94:95], s[96:97], s[94:95]
	v_cmp_gt_i32_e64 s[90:91], 24, v215
	s_and_b64 s[92:93], s[94:95], s[92:93]
	v_cmp_gt_i32_e64 s[88:89], 19, v215
	s_and_b64 s[90:91], s[92:93], s[90:91]
	v_cmp_gt_i32_e64 s[86:87], 18, v215
	s_and_b64 s[88:89], s[90:91], s[88:89]
	v_cmp_gt_i32_e64 s[84:85], 17, v215
	s_and_b64 s[86:87], s[88:89], s[86:87]
	v_cmp_gt_i32_e64 s[82:83], 16, v215
	s_and_b64 s[84:85], s[86:87], s[84:85]
	v_cmp_gt_i32_e64 s[80:81], 11, v215
	s_and_b64 s[82:83], s[84:85], s[82:83]
	v_cmp_gt_i32_e64 s[78:79], 10, v215
	s_and_b64 s[80:81], s[82:83], s[80:81]
	v_cmp_gt_i32_e64 s[76:77], 9, v215
	s_and_b64 s[78:79], s[80:81], s[78:79]
	v_cmp_gt_i32_e64 s[74:75], 8, v215
	s_and_b64 s[76:77], s[78:79], s[76:77]
	v_cmp_gt_i32_e64 s[72:73], 3, v215
	s_and_b64 s[74:75], s[76:77], s[74:75]
	v_cmp_gt_i32_e64 s[70:71], 2, v215
	s_and_b64 s[72:73], s[74:75], s[72:73]
	v_cmp_gt_i32_e64 s[66:67], 1, v215
	s_and_b64 s[70:71], s[72:73], s[70:71]
	v_cmp_gt_i32_e64 s[64:65], 0, v215
	s_and_b64 s[66:67], s[70:71], s[66:67]
	s_and_b64 s[64:65], s[66:67], s[64:65]
	v_cmp_gt_i32_e64 s[62:63], 58, v215
	v_cndmask_b32_e64 v130, v130, v225, s[64:65]
	v_cmp_gt_i32_e64 s[64:65], 59, v215
	v_cmp_gt_i32_e64 s[60:61], 57, v215
	s_and_b64 s[62:63], s[64:65], s[62:63]
	v_cmp_gt_i32_e64 s[58:59], 56, v215
	s_and_b64 s[60:61], s[62:63], s[60:61]
	v_cmp_gt_i32_e64 s[56:57], 51, v215
	s_and_b64 s[58:59], s[60:61], s[58:59]
	v_cmp_gt_i32_e64 s[54:55], 50, v215
	s_and_b64 s[56:57], s[58:59], s[56:57]
	v_cmp_gt_i32_e64 s[52:53], 49, v215
	s_and_b64 s[54:55], s[56:57], s[54:55]
	v_cmp_gt_i32_e64 s[50:51], 48, v215
	s_and_b64 s[52:53], s[54:55], s[52:53]
	v_cmp_gt_i32_e64 s[48:49], 43, v215
	s_and_b64 s[50:51], s[52:53], s[50:51]
	v_cmp_gt_i32_e64 s[46:47], 42, v215
	s_and_b64 s[48:49], s[50:51], s[48:49]
	v_cmp_gt_i32_e64 s[44:45], 41, v215
	s_and_b64 s[46:47], s[48:49], s[46:47]
	v_cmp_gt_i32_e64 s[42:43], 40, v215
	s_and_b64 s[44:45], s[46:47], s[44:45]
	v_cmp_gt_i32_e64 s[40:41], 35, v215
	s_and_b64 s[42:43], s[44:45], s[42:43]
	v_cmp_gt_i32_e64 s[36:37], 34, v215
	s_and_b64 s[40:41], s[42:43], s[40:41]
	v_cmp_gt_i32_e64 s[0:1], 33, v215
	s_and_b64 s[36:37], s[40:41], s[36:37]
	v_cmp_gt_i32_e32 vcc, 32, v215
	s_and_b64 s[0:1], s[36:37], s[0:1]
	s_and_b64 vcc, s[0:1], vcc
	v_cndmask_b32_e64 v145, v145, v225, s[96:97]
	v_cndmask_b32_e64 v144, v144, v225, s[94:95]
	v_cndmask_b32_e64 v143, v143, v225, s[92:93]
	v_cndmask_b32_e64 v142, v142, v225, s[90:91]
	v_cndmask_b32_e64 v141, v141, v225, s[88:89]
	v_cndmask_b32_e64 v140, v140, v225, s[86:87]
	v_cndmask_b32_e64 v139, v139, v225, s[84:85]
	v_cndmask_b32_e64 v138, v138, v225, s[82:83]
	v_cndmask_b32_e64 v137, v137, v225, s[80:81]
	v_cndmask_b32_e64 v136, v136, v225, s[78:79]
	v_cndmask_b32_e64 v135, v135, v225, s[76:77]
	v_cndmask_b32_e64 v134, v134, v225, s[74:75]
	v_cndmask_b32_e64 v133, v133, v225, s[72:73]
	v_cndmask_b32_e64 v132, v132, v225, s[70:71]
	v_cndmask_b32_e64 v131, v131, v225, s[66:67]
	v_cndmask_b32_e64 v161, v161, v225, s[64:65]
	v_cndmask_b32_e64 v160, v160, v225, s[62:63]
	v_cndmask_b32_e64 v159, v159, v225, s[60:61]
	v_cndmask_b32_e64 v158, v158, v225, s[58:59]
	v_cndmask_b32_e64 v157, v157, v225, s[56:57]
	v_cndmask_b32_e64 v156, v156, v225, s[54:55]
	v_cndmask_b32_e64 v155, v155, v225, s[52:53]
	v_cndmask_b32_e64 v154, v154, v225, s[50:51]
	v_cndmask_b32_e64 v153, v153, v225, s[48:49]
	v_cndmask_b32_e64 v152, v152, v225, s[46:47]
	v_cndmask_b32_e64 v151, v151, v225, s[44:45]
	v_cndmask_b32_e64 v150, v150, v225, s[42:43]
	v_cndmask_b32_e64 v149, v149, v225, s[40:41]
	v_cndmask_b32_e64 v148, v148, v225, s[36:37]
	v_cndmask_b32_e64 v147, v147, v225, s[0:1]
	v_cndmask_b32_e32 v146, v146, v225, vcc
	s_branch .LBB0_143
